# speedup vs baseline: 1.0704x; 1.0115x over previous
; #define WAIT_V(n) asm volatile("s_waitcnt vmcnt(" #n ")" ::: "memory")
; #define BAR __builtin_amdgcn_s_barrier()
;     ...
;     f32x4 acc[2][2][4][2] = {};
;     bf16x8 At[4][2], B0[2][2], B1[2][2];
;     if (wr_s == 1) BAR;
;     if (first) WAIT_V(6); else WAIT_V(0);
;     BAR; BAR;
.LBB0_940:
	s_add_i32 s18, s70, 0x80
	v_lshl_add_u64 v[2:3], s[54:55], 0, v[136:137]
	v_mov_b32_e32 v6, s18
	v_lshl_add_u64 v[4:5], s[54:55], 0, v[138:139]
	v_mad_i64_i32 v[140:141], s[2:3], s83, v6, v[2:3]
	v_mad_i64_i32 v[142:143], s[2:3], s83, v6, v[4:5]
	v_lshl_add_u64 v[6:7], s[52:53], 0, v[136:137]
	v_mov_b32_e32 v10, s86
	v_lshl_add_u64 v[8:9], s[52:53], 0, v[138:139]
	s_add_i32 s4, s86, 0x80
	v_mad_i64_i32 v[144:145], s[2:3], s83, v10, v[6:7]
	v_mad_i64_i32 v[146:147], s[2:3], s83, v10, v[8:9]
	v_mov_b32_e32 v10, s70
	v_mad_i64_i32 v[148:149], s[2:3], s83, v10, v[2:3]
	v_mov_b32_e32 v2, s4
	v_mad_i64_i32 v[150:151], s[2:3], s83, v10, v[4:5]
	v_mad_i64_i32 v[152:153], s[2:3], s83, v2, v[6:7]
	v_mad_i64_i32 v[154:155], s[2:3], s83, v2, v[8:9]
	v_mov_b32_e32 v2, 0
	s_ashr_i32 s71, s70, 31
	s_mov_b32 s5, 0
	s_mov_b64 s[2:3], 0
	v_mov_b32_e32 v3, v2
	v_mov_b32_e32 v4, v2
	v_mov_b32_e32 v5, v2
	v_mov_b32_e32 v6, v2
	v_mov_b32_e32 v7, v2
	v_mov_b32_e32 v8, v2
	v_mov_b32_e32 v9, v2
	v_mov_b32_e32 v10, v2
	v_mov_b32_e32 v11, v2
	v_mov_b32_e32 v12, v2
	v_mov_b32_e32 v13, v2
	v_mov_b32_e32 v14, v2
	v_mov_b32_e32 v15, v2
	v_mov_b32_e32 v16, v2
	v_mov_b32_e32 v17, v2
	v_mov_b32_e32 v18, v2
	v_mov_b32_e32 v19, v2
	v_mov_b32_e32 v20, v2
	v_mov_b32_e32 v21, v2
	v_mov_b32_e32 v22, v2
	v_mov_b32_e32 v23, v2
	v_mov_b32_e32 v24, v2
	v_mov_b32_e32 v25, v2
	v_mov_b32_e32 v26, v2
	v_mov_b32_e32 v27, v2
	v_mov_b32_e32 v28, v2
	v_mov_b32_e32 v29, v2
	v_mov_b32_e32 v30, v2
	v_mov_b32_e32 v31, v2
	v_mov_b32_e32 v32, v2
	v_mov_b32_e32 v33, v2
	v_mov_b32_e32 v34, v2
	v_mov_b32_e32 v35, v2
	v_mov_b32_e32 v36, v2
	v_mov_b32_e32 v37, v2
	v_mov_b32_e32 v38, v2
	v_mov_b32_e32 v39, v2
	v_mov_b32_e32 v40, v2
	v_mov_b32_e32 v41, v2
	v_mov_b32_e32 v42, v2
	v_mov_b32_e32 v43, v2
	v_mov_b32_e32 v44, v2
	v_mov_b32_e32 v45, v2
	v_mov_b32_e32 v46, v2
	v_mov_b32_e32 v47, v2
	v_mov_b32_e32 v48, v2
	v_mov_b32_e32 v49, v2
	v_mov_b32_e32 v50, v2
	v_mov_b32_e32 v51, v2
	v_mov_b32_e32 v52, v2
	v_mov_b32_e32 v53, v2
	v_mov_b32_e32 v54, v2
	v_mov_b32_e32 v55, v2
	v_mov_b32_e32 v56, v2
	v_mov_b32_e32 v57, v2
	v_mov_b32_e32 v58, v2
	v_mov_b32_e32 v59, v2
	v_mov_b32_e32 v60, v2
	v_mov_b32_e32 v61, v2
	v_mov_b32_e32 v62, v2
	v_mov_b32_e32 v63, v2
	v_mov_b32_e32 v64, v2
	v_mov_b32_e32 v65, v2
	v_mov_b32_e32 v66, v2
	v_mov_b32_e32 v67, v2
	v_mov_b32_e32 v68, v2
	v_mov_b32_e32 v69, v2
	v_mov_b32_e32 v70, v2
	v_mov_b32_e32 v71, v2
	v_mov_b32_e32 v72, v2
	v_mov_b32_e32 v73, v2
	v_mov_b32_e32 v74, v2
	v_mov_b32_e32 v75, v2
	v_mov_b32_e32 v76, v2
	v_mov_b32_e32 v77, v2
	v_mov_b32_e32 v78, v2
	v_mov_b32_e32 v79, v2
	v_mov_b32_e32 v80, v2
	v_mov_b32_e32 v81, v2
	v_mov_b32_e32 v82, v2
	v_mov_b32_e32 v83, v2
	v_mov_b32_e32 v84, v2
	v_mov_b32_e32 v85, v2
	v_mov_b32_e32 v86, v2
	v_mov_b32_e32 v87, v2
	v_mov_b32_e32 v88, v2
	v_mov_b32_e32 v89, v2
	v_mov_b32_e32 v90, v2
	v_mov_b32_e32 v91, v2
	v_mov_b32_e32 v92, v2
	v_mov_b32_e32 v93, v2
	v_mov_b32_e32 v94, v2
	v_mov_b32_e32 v95, v2
	v_mov_b32_e32 v96, v2
	v_mov_b32_e32 v97, v2
	v_mov_b32_e32 v98, v2
	v_mov_b32_e32 v99, v2
	v_mov_b32_e32 v100, v2
	v_mov_b32_e32 v101, v2
	v_mov_b32_e32 v102, v2
	v_mov_b32_e32 v103, v2
	v_mov_b32_e32 v104, v2
	v_mov_b32_e32 v105, v2
	v_mov_b32_e32 v106, v2
	v_mov_b32_e32 v107, v2
	v_mov_b32_e32 v108, v2
	v_mov_b32_e32 v109, v2
	v_mov_b32_e32 v110, v2
	v_mov_b32_e32 v111, v2
	v_mov_b32_e32 v112, v2
	v_mov_b32_e32 v113, v2
	v_mov_b32_e32 v114, v2
	v_mov_b32_e32 v115, v2
	v_mov_b32_e32 v116, v2
	v_mov_b32_e32 v117, v2
	v_mov_b32_e32 v118, v2
	v_mov_b32_e32 v119, v2
	v_mov_b32_e32 v120, v2
	v_mov_b32_e32 v121, v2
	v_mov_b32_e32 v122, v2
	v_mov_b32_e32 v123, v2
	v_mov_b32_e32 v124, v2
	v_mov_b32_e32 v125, v2
	v_mov_b32_e32 v126, v2
	v_mov_b32_e32 v127, v2
	v_mov_b32_e32 v128, v2
	v_mov_b32_e32 v129, v2
	s_waitcnt vmcnt(0)
	s_barrier
	s_barrier

;     ...
;     if (!has_next) break;
;     first = false;
;   }
.LBB0_953:
	s_xor_b64 s[4:5], s[50:51], -1
	s_mov_b64 s[2:3], -1
	s_and_b64 vcc, exec, s[4:5]
	s_cbranch_vccz .LBB0_938
.LBB0_954:
	s_cbranch_execz .LBB0_939
	s_branch .LBB0_940
.LBB0_955:
	s_mov_b64 s[6:7], -1
	s_mov_b64 s[16:17], 0

; __device__ __forceinline__ uint2 pack4(f32x4 v) { return make_uint2(pack2(v[0], v[1]), pack2(v[2], v[3])); }
;     ...
;     if (mode == E_UPC) {
;       char* st = reinterpret_cast<char*>(shm);
;       float* outl = p->out; char* wsl = p->ws;
;       asm volatile("" : "+s"(outl), "+s"(wsl));
;       const int chb = (cur_bcol >> 8) * 128;
;       int tid = TIDX;
;       asm volatile("" : "+v"(tid));
;       {
;         const int l2 = tid & 63, w2 = tid >> 6;
;         int rloc = (w2 >> 2) * 64 + (l2 & 15), cloc = (w2 & 3) * 32 + (l2 >> 4) * 4;
; #pragma unroll
;         for (int ai = 0; ai < 2; ++ai)
; #pragma unroll
;           for (int bj = 0; bj < 2; ++bj)
; #pragma unroll
;             for (int m = 0; m < 4; ++m) {
; #pragma unroll
;               for (int n = 0; n < 2; ++n) {
;                 const int row = rloc + ai * HALF + m * 16, col = cloc + bj * HALF + n * 16;
;                 const f32x4 v = acc[ai][bj][m][n];
;                 *reinterpret_cast<uint2*>(st + row * 512 + ((((col >> 3) ^ (row & 31))) << 4) + (col & 7) * 2) = pack4(v);
;                 const int rg = g0 + cur_brow + row;
;                 const int ocol = chb + (col & 127) + (col >= 128 ? DFF : 0);
;                 if (rg < NPROMPT) {
.LBB0_997:
	s_and_b64 vcc, exec, s[6:7]
	s_cbranch_vccz .LBB0_935
	s_load_dwordx2 s[2:3], s[0:1], 0xb8
	s_load_dwordx2 s[74:75], s[0:1], 0xc0
	v_mov_b32_e32 v149, v213
	s_movk_i32 s4, 0xffc0
	v_cvt_pk_bf16_f32 v144, v126, v127
	v_cvt_pk_bf16_f32 v145, v128, v129
	s_waitcnt lgkmcnt(0)
	v_readlane_b32 s66, v255, 18
	s_nop 0
	s_add_i32 s85, s86, s66
	s_cmp_lt_i32 s85, 0x10000
	s_cselect_b32 s67, 1, 0
	s_and_b32 s66, s85, 0x7ff
	s_cmp_lg_u32 s66, 0
	s_cselect_b32 s66, 1, 0
	s_and_b32 s67, s67, s66
	s_add_i32 s66, s85, 0x100
	s_and_b32 s66, s66, 0x7ff
	s_cmp_lg_u32 s66, 0
	s_cselect_b32 s66, 1, 0
	s_and_b32 s67, s67, s66
	s_cmp_lg_u32 s67, 0
	s_cbranch_scc1 .Lupc_stage_fast_p
	s_mov_b64 s[6:7], 0
	v_ashrrev_i32_e32 v140, 2, v149
	v_and_b32_e32 v148, 15, v149
	v_and_or_b32 v150, v140, s4, v148
	v_lshrrev_b32_e32 v140, 2, v149
	v_lshrrev_b32_e32 v141, 1, v149
	v_and_b32_e32 v140, 12, v140
	s_movk_i32 s4, 0x60
	v_and_or_b32 v140, v141, s4, v140
	v_readlane_b32 s4, v255, 18
	s_add_i32 s85, s86, s4
	s_add_u32 s66, s2, 0x30760000
	v_lshrrev_b32_e32 v154, 3, v140
	v_and_b32_e32 v151, 8, v141
	s_addc_u32 s67, s3, 0
	v_add_u32_e32 v141, s86, v148
	v_bitop3_b32 v143, v154, v149, 15 bitop3:0x78
	s_add_u32 s94, s2, 0x30200000
	v_and_b32_e32 v142, 63, v141
	v_lshl_or_b32 v155, v150, 9, v151
	v_add_u32_e32 v141, s85, v150
	v_lshlrev_b32_e32 v152, 4, v143
	s_addc_u32 s95, s3, 0
	v_cmp_lt_i32_e64 s[2:3], s78, v141
	v_cmp_lt_u32_e32 vcc, 61, v142
	v_or_b32_e32 v143, v155, v152
	ds_write_b64 v143, v[144:145]
	s_and_saveexec_b64 s[4:5], s[2:3]
	s_xor_b64 s[4:5], exec, s[4:5]
	s_and_b64 s[6:7], vcc, exec
	s_or_saveexec_b64 s[8:9], s[4:5]
	v_add_u32_e32 v143, 0xffff0000, v141
	v_lshrrev_b32_e32 v143, 5, v143
	v_and_b32_e32 v143, 0x7fffffe, v143
	v_subrev_u32_e32 v153, 62, v142
	v_add_u32_e32 v144, v143, v153
	v_mov_b64_e32 v[142:143], s[66:67]
	v_mad_u64_u32 v[142:143], s[4:5], v144, s64, v[142:143]
	v_and_b32_e32 v146, 0x7ff, v141
	s_movk_i32 s4, 0x7fd
	v_ashrrev_i32_e32 v144, 11, v141
	v_cmp_lt_u32_e64 s[4:5], s4, v146
	v_ashrrev_i32_e32 v145, 31, v144
	v_add_u32_e32 v146, 0xfffff802, v146
	v_mov_b32_e32 v147, v0
	v_lshl_add_u64 v[146:147], v[144:145], 1, v[146:147]
	v_mov_b64_e32 v[144:145], s[94:95]
	v_mad_u64_u32 v[144:145], s[10:11], v146, s64, v[144:145]
	v_mad_i32_i24 v145, v147, s64, v145
	v_mov_b64_e32 v[146:147], v[142:143]
	s_xor_b64 exec, exec, s[8:9]
	s_andn2_b64 s[6:7], s[6:7], exec
	s_and_b64 s[10:11], s[4:5], exec
	s_or_b64 s[6:7], s[6:7], s[10:11]
	v_mov_b64_e32 v[146:147], v[144:145]
	s_or_b64 exec, exec, s[8:9]
	s_ashr_i32 s8, s70, 1
	s_and_b32 s60, s8, 0xffffff80
	v_or_b32_e32 v140, s60, v140
	v_ashrrev_i32_e32 v141, 31, v140
	s_and_saveexec_b64 s[8:9], s[6:7]
	s_cbranch_execz .LBB0_1004
	v_lshl_add_u64 v[146:147], v[140:141], 2, v[146:147]
	s_waitcnt vmcnt(0)
	flat_store_dwordx4 v[146:147], v[126:129]

; #define GAS __attribute__((address_space(1)))
;     ...
;       __syncthreads();
;       if (tid < 128) {
;         const int ri = tid >> 5, c16 = tid & 31;
;         const int row = ri < 2 ? ri : 252 + ri;
;         const uint4 v = *reinterpret_cast<const uint4*>(st + row * 512 + ((c16 ^ (row & 31)) << 4));
;         *(GAS uint4*)((u16*)(wsl + W_UPB) + ((size_t)(cur_brow >> 8) * 4 + ri) * UPW + cur_bcol + c16 * 8) = v;
;       }
.Lupc_after_stage_p:
	s_movk_i32 s2, 0x80
	v_cmp_gt_i32_e32 vcc, s2, v149
	s_waitcnt vmcnt(0) lgkmcnt(0)
	s_barrier
	s_and_saveexec_b64 s[2:3], vcc
	s_cbranch_execz .LBB0_1148
	v_ashrrev_i32_e32 v6, 5, v149
	v_add_u32_e32 v2, 0xfc, v6
	v_cmp_gt_i32_e32 vcc, 2, v6
	s_ashr_i32 s4, s86, 8
	v_lshl_add_u32 v8, s4, 2, v6
	v_cndmask_b32_e32 v2, v2, v6, vcc
	v_xor_b32_e32 v3, v2, v149
	v_lshlrev_b32_e32 v3, 4, v3
	v_and_b32_e32 v3, 0x1f0, v3
	v_lshl_or_b32 v2, v2, 9, v3
	v_mov_b64_e32 v[6:7], s[74:75]
	ds_read_b128 v[2:5], v2
	v_mad_i64_i32 v[6:7], s[4:5], v8, s61, v[6:7]
	v_lshlrev_b32_e32 v8, 4, v149
	v_lshl_add_u64 v[6:7], s[70:71], 1, v[6:7]
	v_and_b32_e32 v8, 0x1f0, v8
	v_mov_b32_e32 v9, v0
	v_lshl_add_u64 v[6:7], v[6:7], 0, v[8:9]
	v_add_co_u32_e32 v6, vcc, 0x24c0000, v6
	s_nop 1
	v_addc_co_u32_e32 v7, vcc, 0, v7, vcc
	s_waitcnt lgkmcnt(0)
	flat_store_dwordx4 v[6:7], v[2:5]

; #define PROLOGUE_ISSUE(brow_, bcol_) do { \
;       STAGE(SB(0, 0), Bt, bcol_, 0); STAGE(SA(0, 0), A, brow_, 0); \
;       STAGE(SB(0, 1), Bt, bcol_ + HALF, 0); STAGE(SA(0, 1), A, brow_ + HALF, 0); \
;       STAGE(SB(1, 0), Bt, bcol_, 1); STAGE(SA(1, 0), A, brow_, 1); STAGE(SB(1, 1), Bt, bcol_ + HALF, 1); } while (0)
;     ...
;       __syncthreads();
;       if (has_next) PROLOGUE_ISSUE(brow, bcol);
;       if (!has_next) break;
;       first = false;
;       continue;
.LBB0_1246:
	s_mov_b32 s8, 35
	s_and_b64 vcc, exec, s[56:57]
	s_waitcnt lgkmcnt(0)
	s_barrier
	s_cbranch_vccz .LBB0_934
	s_mul_hi_i32 s3, s82, s34
	s_mul_i32 s2, s82, s34
	s_lshl_b64 s[2:3], s[2:3], 1
	s_add_u32 s2, s54, s2
	s_addc_u32 s3, s55, s3
	v_lshl_add_u64 v[2:3], s[2:3], 0, v[132:133]
	v_lshl_add_u64 v[4:5], s[2:3], 0, v[134:135]
	s_mul_hi_i32 s3, s87, s34
	s_mul_i32 s2, s87, s34
	s_lshl_b64 s[2:3], s[2:3], 1
	s_add_u32 s2, s52, s2
	s_addc_u32 s3, s53, s3
	v_lshl_add_u64 v[6:7], s[2:3], 0, v[132:133]
	v_lshl_add_u64 v[8:9], s[2:3], 0, v[134:135]
	s_or_b32 s2, s82, 0x80
	s_mul_hi_i32 s3, s2, s34
	s_mul_i32 s2, s2, s34
	s_lshl_b64 s[2:3], s[2:3], 1
	s_add_u32 s2, s54, s2
	s_mov_b32 m0, s39
	s_addc_u32 s3, s55, s3
	global_load_lds_dwordx4 v[2:3], off
	s_mov_b32 m0, s40
	v_lshl_add_u64 v[10:11], s[2:3], 0, v[132:133]
	v_lshl_add_u64 v[12:13], s[2:3], 0, v[134:135]
	s_or_b32 s2, s87, 0x80
	global_load_lds_dwordx4 v[4:5], off
	s_mov_b32 m0, s24
	s_mul_hi_i32 s3, s2, s34
	s_mul_i32 s2, s2, s34
	global_load_lds_dwordx4 v[6:7], off
	s_mov_b32 m0, s41
	s_lshl_b64 s[2:3], s[2:3], 1
	global_load_lds_dwordx4 v[8:9], off
	s_mov_b32 m0, s62
	s_add_u32 s2, s52, s2
	global_load_lds_dwordx4 v[10:11], off
	s_mov_b32 m0, s44
	s_addc_u32 s3, s53, s3
	global_load_lds_dwordx4 v[12:13], off
	v_lshl_add_u64 v[14:15], s[2:3], 0, v[132:133]
	s_mov_b32 m0, s45
	v_lshl_add_u64 v[2:3], v[2:3], 0, s[90:91]
	global_load_lds_dwordx4 v[14:15], off
	v_lshl_add_u64 v[14:15], s[2:3], 0, v[134:135]
	s_mov_b32 m0, s38
	s_mov_b32 s8, 34
	global_load_lds_dwordx4 v[14:15], off
	s_mov_b32 m0, s28
	s_nop 0
	global_load_lds_dwordx4 v[2:3], off
	v_lshl_add_u64 v[2:3], v[4:5], 0, s[90:91]
	s_mov_b32 m0, s29
	s_nop 0
	global_load_lds_dwordx4 v[2:3], off
	v_lshl_add_u64 v[2:3], v[6:7], 0, s[90:91]
	s_mov_b32 m0, s36
	s_nop 0
	global_load_lds_dwordx4 v[2:3], off
	v_lshl_add_u64 v[2:3], v[8:9], 0, s[90:91]
	s_mov_b32 m0, s37
	s_nop 0
	global_load_lds_dwordx4 v[2:3], off
	v_lshl_add_u64 v[2:3], v[10:11], 0, s[90:91]
	s_mov_b32 m0, s26
	s_nop 0
	global_load_lds_dwordx4 v[2:3], off
	v_lshl_add_u64 v[2:3], v[12:13], 0, s[90:91]
	s_mov_b32 m0, s27
	s_nop 0
	global_load_lds_dwordx4 v[2:3], off
	s_branch .LBB0_934

; __device__ __forceinline__ uint2 pack4(f32x4 v) { return make_uint2(pack2(v[0], v[1]), pack2(v[2], v[3])); }
;     ...
;         const int l2 = tid & 63, w2 = tid >> 6;
;         int rloc = (w2 >> 2) * 64 + (l2 & 15), cloc = (w2 & 3) * 32 + (l2 >> 4) * 4;
; #pragma unroll
;         for (int ai = 0; ai < 2; ++ai)
; #pragma unroll
;           for (int bj = 0; bj < 2; ++bj)
; #pragma unroll
;             for (int m = 0; m < 4; ++m) {
; #pragma unroll
;               for (int n = 0; n < 2; ++n) {
;                 const int row = rloc + ai * HALF + m * 16, col = cloc + bj * HALF + n * 16;
;                 const f32x4 v = acc[ai][bj][m][n];
;                 *reinterpret_cast<uint2*>(st + row * 512 + ((((col >> 3) ^ (row & 31))) << 4) + (col & 7) * 2) = pack4(v);
.Lupc_stage_fast_p:
	v_and_b32_e32 v140, 15, v149
	v_bfe_u32 v141, v149, 4, 2
	v_lshrrev_b32_e32 v142, 6, v149
	v_and_b32_e32 v143, 3, v142
	v_lshrrev_b32_e32 v142, 2, v142
	v_lshl_add_u32 v142, v142, 6, v140
	v_lshrrev_b32_e32 v144, 1, v141
	v_lshl_add_u32 v143, v143, 2, v144
	v_xor_b32_e32 v143, v143, v140
	v_lshlrev_b32_e32 v143, 4, v143
	v_and_b32_e32 v144, 1, v141
	v_lshl_or_b32 v143, v144, 3, v143
	v_lshl_or_b32 v143, v142, 9, v143
	v_xor_b32_e32 v144, 32, v143
	v_xor_b32_e32 v145, 0x100, v143
	v_xor_b32_e32 v146, 0x120, v143
	v_add_u32_e32 v150, 0x10000, v143
	v_add_u32_e32 v151, 0x10000, v144
	v_add_u32_e32 v152, 0x10000, v145
	v_add_u32_e32 v153, 0x10000, v146
	v_cvt_pk_bf16_f32 v154, v126, v127
	v_cvt_pk_bf16_f32 v155, v128, v129
	ds_write_b64 v143, v[154:155]
	v_cvt_pk_bf16_f32 v156, v122, v123
	v_cvt_pk_bf16_f32 v157, v124, v125
	ds_write_b64 v144, v[156:157]
	v_cvt_pk_bf16_f32 v158, v118, v119
	v_cvt_pk_bf16_f32 v159, v120, v121
	ds_write_b64 v145, v[158:159] offset:8192
	v_cvt_pk_bf16_f32 v160, v114, v115
	v_cvt_pk_bf16_f32 v161, v116, v117
	ds_write_b64 v146, v[160:161] offset:8192
	v_cvt_pk_bf16_f32 v154, v110, v111
	v_cvt_pk_bf16_f32 v155, v112, v113
	ds_write_b64 v143, v[154:155] offset:16384
	v_cvt_pk_bf16_f32 v156, v106, v107
	v_cvt_pk_bf16_f32 v157, v108, v109
	ds_write_b64 v144, v[156:157] offset:16384
	v_cvt_pk_bf16_f32 v158, v102, v103
	v_cvt_pk_bf16_f32 v159, v104, v105
	ds_write_b64 v145, v[158:159] offset:24576
	v_cvt_pk_bf16_f32 v160, v98, v99
	v_cvt_pk_bf16_f32 v161, v100, v101
	ds_write_b64 v146, v[160:161] offset:24576
	v_cvt_pk_bf16_f32 v154, v94, v95
	v_cvt_pk_bf16_f32 v155, v96, v97
	ds_write_b64 v145, v[154:155]
	v_cvt_pk_bf16_f32 v156, v90, v91
	v_cvt_pk_bf16_f32 v157, v92, v93
	ds_write_b64 v146, v[156:157]
	v_cvt_pk_bf16_f32 v158, v86, v87
	v_cvt_pk_bf16_f32 v159, v88, v89
	ds_write_b64 v143, v[158:159] offset:8192
	v_cvt_pk_bf16_f32 v160, v82, v83
	v_cvt_pk_bf16_f32 v161, v84, v85
	ds_write_b64 v144, v[160:161] offset:8192
	v_cvt_pk_bf16_f32 v154, v78, v79
	v_cvt_pk_bf16_f32 v155, v80, v81
	ds_write_b64 v145, v[154:155] offset:16384
	v_cvt_pk_bf16_f32 v156, v74, v75
	v_cvt_pk_bf16_f32 v157, v76, v77
	ds_write_b64 v146, v[156:157] offset:16384
	v_cvt_pk_bf16_f32 v158, v70, v71
	v_cvt_pk_bf16_f32 v159, v72, v73
	ds_write_b64 v143, v[158:159] offset:24576
	v_cvt_pk_bf16_f32 v160, v66, v67
	v_cvt_pk_bf16_f32 v161, v68, v69
	ds_write_b64 v144, v[160:161] offset:24576
	v_cvt_pk_bf16_f32 v154, v62, v63
	v_cvt_pk_bf16_f32 v155, v64, v65
	ds_write_b64 v150, v[154:155]
	v_cvt_pk_bf16_f32 v156, v58, v59
	v_cvt_pk_bf16_f32 v157, v60, v61
	ds_write_b64 v151, v[156:157]
	v_cvt_pk_bf16_f32 v158, v54, v55
	v_cvt_pk_bf16_f32 v159, v56, v57
	ds_write_b64 v152, v[158:159] offset:8192
	v_cvt_pk_bf16_f32 v160, v50, v51
	v_cvt_pk_bf16_f32 v161, v52, v53
	ds_write_b64 v153, v[160:161] offset:8192
	v_cvt_pk_bf16_f32 v154, v46, v47
	v_cvt_pk_bf16_f32 v155, v48, v49
	ds_write_b64 v150, v[154:155] offset:16384
	v_cvt_pk_bf16_f32 v156, v42, v43
	v_cvt_pk_bf16_f32 v157, v44, v45
	ds_write_b64 v151, v[156:157] offset:16384
	v_cvt_pk_bf16_f32 v158, v38, v39
	v_cvt_pk_bf16_f32 v159, v40, v41
	ds_write_b64 v152, v[158:159] offset:24576
	v_cvt_pk_bf16_f32 v160, v34, v35
	v_cvt_pk_bf16_f32 v161, v36, v37
	ds_write_b64 v153, v[160:161] offset:24576
	v_cvt_pk_bf16_f32 v154, v30, v31
	v_cvt_pk_bf16_f32 v155, v32, v33
	ds_write_b64 v152, v[154:155]
	v_cvt_pk_bf16_f32 v156, v26, v27
	v_cvt_pk_bf16_f32 v157, v28, v29
	ds_write_b64 v153, v[156:157]
	v_cvt_pk_bf16_f32 v158, v22, v23
	v_cvt_pk_bf16_f32 v159, v24, v25
	ds_write_b64 v150, v[158:159] offset:8192
	v_cvt_pk_bf16_f32 v160, v18, v19
	v_cvt_pk_bf16_f32 v161, v20, v21
	ds_write_b64 v151, v[160:161] offset:8192
	v_cvt_pk_bf16_f32 v154, v14, v15
	v_cvt_pk_bf16_f32 v155, v16, v17
	ds_write_b64 v152, v[154:155] offset:16384
	v_cvt_pk_bf16_f32 v156, v10, v11
	v_cvt_pk_bf16_f32 v157, v12, v13
	ds_write_b64 v153, v[156:157] offset:16384
	v_cvt_pk_bf16_f32 v158, v6, v7
	v_cvt_pk_bf16_f32 v159, v8, v9
	ds_write_b64 v150, v[158:159] offset:24576
	v_cvt_pk_bf16_f32 v160, v2, v3
	v_cvt_pk_bf16_f32 v161, v4, v5
	ds_write_b64 v151, v[160:161] offset:24576
	s_branch .Lupc_after_stage_p
